# v59 with odd-XCD P1 stagger shortened 13us -> 5us
# speedup vs baseline: 1.0021x; 1.0021x over previous
.LBB0_255:
	s_or_b64 exec, exec, s[4:5]
	s_cmpk_lt_i32 s97, 0xc00
	v_mov_b32_e32 v8, v234
	s_cselect_b64 s[4:5], -1, 0
	s_cmpk_gt_i32 s97, 0xbff
	s_waitcnt lgkmcnt(0)
	s_barrier
	s_bfe_u32 s99, s97, 0x10000
	s_cmp_eq_u32 s99, 0
	s_cbranch_scc1 .Lmy_p1_nodelay
	s_mul_i32 s99, s99, 500
	s_memrealtime s[100:101]
	s_waitcnt lgkmcnt(0)
	s_add_u32 s98, s100, s99
